# PEER expert lists sorted by expert id per token, rotated to a per-XCD leader-published phase pointer for L2 locality
# speedup vs baseline: 1.0656x; 1.0644x over previous
.LBB0_473:
	s_waitcnt vmcnt(0)
	s_and_b32 s2, s96, 7
	s_lshl_b32 s2, s2, 7
	s_add_u32 s2, s2, s44
	s_addc_u32 s3, s45, 0
	s_add_u32 s2, s2, 0xffff8100
	s_addc_u32 s3, s3, -1
	v_mov_b32_e32 v224, s2
	v_mov_b32_e32 v225, s3
	global_load_dword v234, v[224:225], off sc1
	v_lshl_or_b32 v226, v59, 7, v60
	v_lshlrev_b32_e32 v227, 7, v89
	v_or3_b32 v227, v227, v60, 64
	ds_bpermute_b32 v228, v122, v226
	ds_bpermute_b32 v229, v122, v227
	s_mov_b32 vcc_lo, 0x99999999
	s_mov_b32 vcc_hi, 0x99999999
	s_waitcnt lgkmcnt(0)
	v_min_u32_e32 v230, v226, v228
	v_max_u32_e32 v231, v226, v228
	v_min_u32_e32 v232, v227, v229
	v_max_u32_e32 v233, v227, v229
	v_cndmask_b32_e32 v226, v231, v230, vcc
	v_cndmask_b32_e32 v227, v233, v232, vcc
	ds_bpermute_b32 v228, v123, v226
	ds_bpermute_b32 v229, v123, v227
	s_mov_b32 vcc_lo, 0xc3c3c3c3
	s_mov_b32 vcc_hi, 0xc3c3c3c3
	s_waitcnt lgkmcnt(0)
	v_min_u32_e32 v230, v226, v228
	v_max_u32_e32 v231, v226, v228
	v_min_u32_e32 v232, v227, v229
	v_max_u32_e32 v233, v227, v229
	v_cndmask_b32_e32 v226, v231, v230, vcc
	v_cndmask_b32_e32 v227, v233, v232, vcc
	ds_bpermute_b32 v228, v122, v226
	ds_bpermute_b32 v229, v122, v227
	s_mov_b32 vcc_lo, 0xa5a5a5a5
	s_mov_b32 vcc_hi, 0xa5a5a5a5
	s_waitcnt lgkmcnt(0)
	v_min_u32_e32 v230, v226, v228
	v_max_u32_e32 v231, v226, v228
	v_min_u32_e32 v232, v227, v229
	v_max_u32_e32 v233, v227, v229
	v_cndmask_b32_e32 v226, v231, v230, vcc
	v_cndmask_b32_e32 v227, v233, v232, vcc
	ds_bpermute_b32 v228, v124, v226
	ds_bpermute_b32 v229, v124, v227
	s_mov_b32 vcc_lo, 0xf00ff00f
	s_mov_b32 vcc_hi, 0xf00ff00f
	s_waitcnt lgkmcnt(0)
	v_min_u32_e32 v230, v226, v228
	v_max_u32_e32 v231, v226, v228
	v_min_u32_e32 v232, v227, v229
	v_max_u32_e32 v233, v227, v229
	v_cndmask_b32_e32 v226, v231, v230, vcc
	v_cndmask_b32_e32 v227, v233, v232, vcc
	ds_bpermute_b32 v228, v123, v226
	ds_bpermute_b32 v229, v123, v227
	s_mov_b32 vcc_lo, 0xcc33cc33
	s_mov_b32 vcc_hi, 0xcc33cc33
	s_waitcnt lgkmcnt(0)
	v_min_u32_e32 v230, v226, v228
	v_max_u32_e32 v231, v226, v228
	v_min_u32_e32 v232, v227, v229
	v_max_u32_e32 v233, v227, v229
	v_cndmask_b32_e32 v226, v231, v230, vcc
	v_cndmask_b32_e32 v227, v233, v232, vcc
	ds_bpermute_b32 v228, v122, v226
	ds_bpermute_b32 v229, v122, v227
	s_mov_b32 vcc_lo, 0xaa55aa55
	s_mov_b32 vcc_hi, 0xaa55aa55
	s_waitcnt lgkmcnt(0)
	v_min_u32_e32 v230, v226, v228
	v_max_u32_e32 v231, v226, v228
	v_min_u32_e32 v232, v227, v229
	v_max_u32_e32 v233, v227, v229
	v_cndmask_b32_e32 v226, v231, v230, vcc
	v_cndmask_b32_e32 v227, v233, v232, vcc
	ds_bpermute_b32 v228, v125, v226
	ds_bpermute_b32 v229, v125, v227
	s_mov_b32 vcc_lo, 0xff0000ff
	s_mov_b32 vcc_hi, 0xff0000ff
	s_waitcnt lgkmcnt(0)
	v_min_u32_e32 v230, v226, v228
	v_max_u32_e32 v231, v226, v228
	v_min_u32_e32 v232, v227, v229
	v_max_u32_e32 v233, v227, v229
	v_cndmask_b32_e32 v226, v231, v230, vcc
	v_cndmask_b32_e32 v227, v233, v232, vcc
	ds_bpermute_b32 v228, v124, v226
	ds_bpermute_b32 v229, v124, v227
	s_mov_b32 vcc_lo, 0xf0f00f0f
	s_mov_b32 vcc_hi, 0xf0f00f0f
	s_waitcnt lgkmcnt(0)
	v_min_u32_e32 v230, v226, v228
	v_max_u32_e32 v231, v226, v228
	v_min_u32_e32 v232, v227, v229
	v_max_u32_e32 v233, v227, v229
	v_cndmask_b32_e32 v226, v231, v230, vcc
	v_cndmask_b32_e32 v227, v233, v232, vcc
	ds_bpermute_b32 v228, v123, v226
	ds_bpermute_b32 v229, v123, v227
	s_mov_b32 vcc_lo, 0xcccc3333
	s_mov_b32 vcc_hi, 0xcccc3333
	s_waitcnt lgkmcnt(0)
	v_min_u32_e32 v230, v226, v228
	v_max_u32_e32 v231, v226, v228
	v_min_u32_e32 v232, v227, v229
	v_max_u32_e32 v233, v227, v229
	v_cndmask_b32_e32 v226, v231, v230, vcc
	v_cndmask_b32_e32 v227, v233, v232, vcc
	ds_bpermute_b32 v228, v122, v226
	ds_bpermute_b32 v229, v122, v227
	s_mov_b32 vcc_lo, 0xaaaa5555
	s_mov_b32 vcc_hi, 0xaaaa5555
	s_waitcnt lgkmcnt(0)
	v_min_u32_e32 v230, v226, v228
	v_max_u32_e32 v231, v226, v228
	v_min_u32_e32 v232, v227, v229
	v_max_u32_e32 v233, v227, v229
	v_cndmask_b32_e32 v226, v231, v230, vcc
	v_cndmask_b32_e32 v227, v233, v232, vcc
	ds_bpermute_b32 v228, v126, v226
	ds_bpermute_b32 v229, v126, v227
	s_mov_b32 vcc_lo, 0x0000ffff
	s_mov_b32 vcc_hi, 0xffff0000
	s_waitcnt lgkmcnt(0)
	v_min_u32_e32 v230, v226, v228
	v_max_u32_e32 v231, v226, v228
	v_min_u32_e32 v232, v227, v229
	v_max_u32_e32 v233, v227, v229
	v_cndmask_b32_e32 v226, v231, v230, vcc
	v_cndmask_b32_e32 v227, v233, v232, vcc
	ds_bpermute_b32 v228, v125, v226
	ds_bpermute_b32 v229, v125, v227
	s_mov_b32 vcc_lo, 0x00ff00ff
	s_mov_b32 vcc_hi, 0xff00ff00
	s_waitcnt lgkmcnt(0)
	v_min_u32_e32 v230, v226, v228
	v_max_u32_e32 v231, v226, v228
	v_min_u32_e32 v232, v227, v229
	v_max_u32_e32 v233, v227, v229
	v_cndmask_b32_e32 v226, v231, v230, vcc
	v_cndmask_b32_e32 v227, v233, v232, vcc
	ds_bpermute_b32 v228, v124, v226
	ds_bpermute_b32 v229, v124, v227
	s_mov_b32 vcc_lo, 0x0f0f0f0f
	s_mov_b32 vcc_hi, 0xf0f0f0f0
	s_waitcnt lgkmcnt(0)
	v_min_u32_e32 v230, v226, v228
	v_max_u32_e32 v231, v226, v228
	v_min_u32_e32 v232, v227, v229
	v_max_u32_e32 v233, v227, v229
	v_cndmask_b32_e32 v226, v231, v230, vcc
	v_cndmask_b32_e32 v227, v233, v232, vcc
	ds_bpermute_b32 v228, v123, v226
	ds_bpermute_b32 v229, v123, v227
	s_mov_b32 vcc_lo, 0x33333333
	s_mov_b32 vcc_hi, 0xcccccccc
	s_waitcnt lgkmcnt(0)
	v_min_u32_e32 v230, v226, v228
	v_max_u32_e32 v231, v226, v228
	v_min_u32_e32 v232, v227, v229
	v_max_u32_e32 v233, v227, v229
	v_cndmask_b32_e32 v226, v231, v230, vcc
	v_cndmask_b32_e32 v227, v233, v232, vcc
	ds_bpermute_b32 v228, v122, v226
	ds_bpermute_b32 v229, v122, v227
	s_mov_b32 vcc_lo, 0x55555555
	s_mov_b32 vcc_hi, 0xaaaaaaaa
	s_waitcnt lgkmcnt(0)
	v_min_u32_e32 v230, v226, v228
	v_max_u32_e32 v231, v226, v228
	v_min_u32_e32 v232, v227, v229
	v_max_u32_e32 v233, v227, v229
	v_cndmask_b32_e32 v226, v231, v230, vcc
	v_cndmask_b32_e32 v227, v233, v232, vcc
	ds_bpermute_b32 v228, v127, v226
	ds_bpermute_b32 v229, v127, v227
	s_mov_b32 vcc_lo, 0xffffffff
	s_mov_b32 vcc_hi, 0x00000000
	s_waitcnt lgkmcnt(0)
	v_min_u32_e32 v230, v226, v228
	v_max_u32_e32 v231, v226, v228
	v_min_u32_e32 v232, v227, v229
	v_max_u32_e32 v233, v227, v229
	v_cndmask_b32_e32 v226, v231, v230, vcc
	v_cndmask_b32_e32 v227, v232, v233, vcc
	ds_bpermute_b32 v228, v126, v226
	ds_bpermute_b32 v229, v126, v227
	s_mov_b32 vcc_lo, 0x0000ffff
	s_mov_b32 vcc_hi, 0x0000ffff
	s_waitcnt lgkmcnt(0)
	v_min_u32_e32 v230, v226, v228
	v_max_u32_e32 v231, v226, v228
	v_min_u32_e32 v232, v227, v229
	v_max_u32_e32 v233, v227, v229
	v_cndmask_b32_e32 v226, v231, v230, vcc
	v_cndmask_b32_e32 v227, v232, v233, vcc
	ds_bpermute_b32 v228, v125, v226
	ds_bpermute_b32 v229, v125, v227
	s_mov_b32 vcc_lo, 0x00ff00ff
	s_mov_b32 vcc_hi, 0x00ff00ff
	s_waitcnt lgkmcnt(0)
	v_min_u32_e32 v230, v226, v228
	v_max_u32_e32 v231, v226, v228
	v_min_u32_e32 v232, v227, v229
	v_max_u32_e32 v233, v227, v229
	v_cndmask_b32_e32 v226, v231, v230, vcc
	v_cndmask_b32_e32 v227, v232, v233, vcc
	ds_bpermute_b32 v228, v124, v226
	ds_bpermute_b32 v229, v124, v227
	s_mov_b32 vcc_lo, 0x0f0f0f0f
	s_mov_b32 vcc_hi, 0x0f0f0f0f
	s_waitcnt lgkmcnt(0)
	v_min_u32_e32 v230, v226, v228
	v_max_u32_e32 v231, v226, v228
	v_min_u32_e32 v232, v227, v229
	v_max_u32_e32 v233, v227, v229
	v_cndmask_b32_e32 v226, v231, v230, vcc
	v_cndmask_b32_e32 v227, v232, v233, vcc
	ds_bpermute_b32 v228, v123, v226
	ds_bpermute_b32 v229, v123, v227
	s_mov_b32 vcc_lo, 0x33333333
	s_mov_b32 vcc_hi, 0x33333333
	s_waitcnt lgkmcnt(0)
	v_min_u32_e32 v230, v226, v228
	v_max_u32_e32 v231, v226, v228
	v_min_u32_e32 v232, v227, v229
	v_max_u32_e32 v233, v227, v229
	v_cndmask_b32_e32 v226, v231, v230, vcc
	v_cndmask_b32_e32 v227, v232, v233, vcc
	ds_bpermute_b32 v228, v122, v226
	ds_bpermute_b32 v229, v122, v227
	s_mov_b32 vcc_lo, 0x55555555
	s_mov_b32 vcc_hi, 0x55555555
	s_waitcnt lgkmcnt(0)
	v_min_u32_e32 v230, v226, v228
	v_max_u32_e32 v231, v226, v228
	v_min_u32_e32 v232, v227, v229
	v_max_u32_e32 v233, v227, v229
	v_cndmask_b32_e32 v226, v231, v230, vcc
	v_cndmask_b32_e32 v227, v232, v233, vcc
	v_min_u32_e32 v230, v226, v227
	v_max_u32_e32 v227, v226, v227
	v_mov_b32_e32 v226, v230
	ds_bpermute_b32 v228, v127, v226
	ds_bpermute_b32 v229, v127, v227
	s_mov_b32 vcc_lo, 0xffffffff
	s_mov_b32 vcc_hi, 0x00000000
	s_waitcnt lgkmcnt(0)
	v_min_u32_e32 v230, v226, v228
	v_max_u32_e32 v231, v226, v228
	v_min_u32_e32 v232, v227, v229
	v_max_u32_e32 v233, v227, v229
	v_cndmask_b32_e32 v226, v231, v230, vcc
	v_cndmask_b32_e32 v227, v233, v232, vcc
	ds_bpermute_b32 v228, v126, v226
	ds_bpermute_b32 v229, v126, v227
	s_mov_b32 vcc_lo, 0x0000ffff
	s_mov_b32 vcc_hi, 0x0000ffff
	s_waitcnt lgkmcnt(0)
	v_min_u32_e32 v230, v226, v228
	v_max_u32_e32 v231, v226, v228
	v_min_u32_e32 v232, v227, v229
	v_max_u32_e32 v233, v227, v229
	v_cndmask_b32_e32 v226, v231, v230, vcc
	v_cndmask_b32_e32 v227, v233, v232, vcc
	ds_bpermute_b32 v228, v125, v226
	ds_bpermute_b32 v229, v125, v227
	s_mov_b32 vcc_lo, 0x00ff00ff
	s_mov_b32 vcc_hi, 0x00ff00ff
	s_waitcnt lgkmcnt(0)
	v_min_u32_e32 v230, v226, v228
	v_max_u32_e32 v231, v226, v228
	v_min_u32_e32 v232, v227, v229
	v_max_u32_e32 v233, v227, v229
	v_cndmask_b32_e32 v226, v231, v230, vcc
	v_cndmask_b32_e32 v227, v233, v232, vcc
	ds_bpermute_b32 v228, v124, v226
	ds_bpermute_b32 v229, v124, v227
	s_mov_b32 vcc_lo, 0x0f0f0f0f
	s_mov_b32 vcc_hi, 0x0f0f0f0f
	s_waitcnt lgkmcnt(0)
	v_min_u32_e32 v230, v226, v228
	v_max_u32_e32 v231, v226, v228
	v_min_u32_e32 v232, v227, v229
	v_max_u32_e32 v233, v227, v229
	v_cndmask_b32_e32 v226, v231, v230, vcc
	v_cndmask_b32_e32 v227, v233, v232, vcc
	ds_bpermute_b32 v228, v123, v226
	ds_bpermute_b32 v229, v123, v227
	s_mov_b32 vcc_lo, 0x33333333
	s_mov_b32 vcc_hi, 0x33333333
	s_waitcnt lgkmcnt(0)
	v_min_u32_e32 v230, v226, v228
	v_max_u32_e32 v231, v226, v228
	v_min_u32_e32 v232, v227, v229
	v_max_u32_e32 v233, v227, v229
	v_cndmask_b32_e32 v226, v231, v230, vcc
	v_cndmask_b32_e32 v227, v233, v232, vcc
	ds_bpermute_b32 v228, v122, v226
	ds_bpermute_b32 v229, v122, v227
	s_mov_b32 vcc_lo, 0x55555555
	s_mov_b32 vcc_hi, 0x55555555
	s_waitcnt lgkmcnt(0)
	v_min_u32_e32 v230, v226, v228
	v_max_u32_e32 v231, v226, v228
	v_min_u32_e32 v232, v227, v229
	v_max_u32_e32 v233, v227, v229
	v_cndmask_b32_e32 v226, v231, v230, vcc
	v_cndmask_b32_e32 v227, v233, v232, vcc
	s_waitcnt vmcnt(0)
	v_readfirstlane_b32 s2, v234
	s_and_b32 s2, s2, 0x3fff
	s_mov_b32 s97, s2
	s_lshl_b32 s3, s2, 7
	v_cmp_gt_u32_e32 vcc, s3, v226
	s_nop 1
	s_bcnt1_i32_b64 s2, vcc
	v_cmp_gt_u32_e32 vcc, s3, v227
	s_nop 1
	s_bcnt1_i32_b64 s3, vcc
	s_add_i32 s2, s2, s3
	s_and_b32 s2, s2, 0x7c
	v_add_u32_e32 v235, s2, v60
	v_and_b32_e32 v235, 0x7f, v235
	v_and_b32_e32 v236, 63, v235
	v_lshlrev_b32_e32 v236, 2, v236
	ds_bpermute_b32 v228, v236, v226
	ds_bpermute_b32 v229, v236, v227
	v_cmp_gt_u32_e32 vcc, 64, v235
	s_waitcnt lgkmcnt(0)
	v_cndmask_b32_e32 v230, v229, v228, vcc
	v_cndmask_b32_e32 v231, v228, v229, vcc
	v_lshrrev_b32_e32 v59, 7, v230
	v_lshrrev_b32_e32 v89, 7, v231
	v_and_b32_e32 v235, 63, v230
	v_lshlrev_b32_e32 v235, 2, v235
	v_and_b32_e32 v236, 63, v231
	v_lshlrev_b32_e32 v236, 2, v236
	ds_bpermute_b32 v240, v235, v128
	ds_bpermute_b32 v241, v235, v129
	ds_bpermute_b32 v242, v236, v128
	ds_bpermute_b32 v243, v236, v129
	v_and_b32_e32 v237, 64, v230
	v_and_b32_e32 v238, 64, v231
	s_waitcnt lgkmcnt(0)
	v_cmp_eq_u32_e32 vcc, 0, v237
	s_nop 1
	v_cndmask_b32_e32 v128, v241, v240, vcc
	v_cmp_eq_u32_e32 vcc, 0, v238
	s_nop 1
	v_cndmask_b32_e32 v129, v243, v242, vcc
	s_nop 1
	v_lshlrev_b32_e32 v84, 16, v4
	v_and_b32_e32 v85, 0xffff0000, v4
	v_lshlrev_b32_e32 v86, 16, v5
	v_and_b32_e32 v87, 0xffff0000, v5
	v_lshlrev_b32_e32 v76, 16, v0
	v_and_b32_e32 v77, 0xffff0000, v0
	v_max3_f32 v0, |v84|, 0, |v85|
	v_lshlrev_b32_e32 v80, 16, v6
	v_and_b32_e32 v81, 0xffff0000, v6
	v_max3_f32 v0, v0, |v86|, |v87|
	v_lshlrev_b32_e32 v82, 16, v7
	v_and_b32_e32 v83, 0xffff0000, v7
	v_max3_f32 v0, v0, |v80|, |v81|
	v_max3_f32 v0, v0, |v82|, |v83|
	v_lshlrev_b32_e32 v78, 16, v1
	v_and_b32_e32 v79, 0xffff0000, v1
	v_max3_f32 v0, v0, |v76|, |v77|
	v_lshlrev_b32_e32 v72, 16, v2
	v_and_b32_e32 v73, 0xffff0000, v2
	v_max3_f32 v0, v0, |v78|, |v79|
	v_lshlrev_b32_e32 v74, 16, v3
	v_and_b32_e32 v75, 0xffff0000, v3
	v_max3_f32 v0, v0, |v72|, |v73|
	v_max3_f32 v0, v0, |v74|, |v75|
	ds_bpermute_b32 v1, v127, v0
	v_or_b32_e32 v88, s23, v58
	s_add_i32 s23, s23, 1
	s_min_u32 s2, s23, 15
	v_or_b32_e32 v8, s2, v62
	s_waitcnt lgkmcnt(0)
	v_max_f32_e32 v1, v1, v1
	v_max_f32_e32 v0, v0, v1
	ds_bpermute_b32 v1, v126, v0
	v_mov_b32_e32 v9, v63
	v_lshl_add_u32 v2, v88, 2, v118
	ds_read_b32 v40, v2
	s_waitcnt vmcnt(3)
	v_readlane_b32 s78, v59, 1
	s_waitcnt lgkmcnt(1)
	v_max_f32_e32 v1, v1, v1
	v_max_f32_e32 v0, v0, v1
	ds_bpermute_b32 v1, v125, v0
	v_readlane_b32 s82, v59, 2
	v_readlane_b32 s86, v59, 3
	s_waitcnt vmcnt(1)
	v_readlane_b32 s33, v128, 0
	v_readlane_b32 s35, v128, 1
	s_waitcnt lgkmcnt(0)
	v_max_f32_e32 v1, v1, v1
	v_max_f32_e32 v10, v0, v1
	ds_bpermute_b32 v11, v124, v10
	v_lshlrev_b64 v[0:1], 11, v[8:9]
	v_lshlrev_b64 v[8:9], 9, v[8:9]
	v_lshl_or_b32 v8, v60, 2, v8
	v_lshl_add_u64 v[4:5], v[70:71], 0, v[0:1]
	s_waitcnt lgkmcnt(0)
	v_max_f32_e32 v11, v11, v11
	v_max_f32_e32 v13, v10, v11
	ds_bpermute_b32 v14, v123, v13
	v_lshl_add_u64 v[10:11], s[12:13], 0, v[8:9]
	v_or_b32_e32 v12, 0x100, v8
	global_load_dwordx4 v[0:3], v[4:5], off offset:16
	s_nop 0
	global_load_dwordx4 v[4:7], v[4:5], off
	v_readlane_b32 s38, v128, 2
	s_waitcnt lgkmcnt(0)
	v_max_f32_e32 v14, v14, v14
	v_max_f32_e32 v16, v13, v14
	ds_bpermute_b32 v17, v122, v16
	v_mov_b32_e32 v13, v9
	v_lshl_add_u64 v[8:9], s[14:15], 0, v[8:9]
	v_lshl_add_u64 v[14:15], s[12:13], 0, v[12:13]
	v_lshl_add_u64 v[12:13], s[14:15], 0, v[12:13]
	s_waitcnt lgkmcnt(0)
	v_max3_f32 v16, v16, v17, s63
	v_div_scale_f32 v17, s[2:3], v16, v16, s64
	v_rcp_f32_e32 v18, v17
	global_load_dword v56, v[10:11], off
	global_load_dword v130, v[14:15], off
	global_load_dword v131, v[8:9], off
	global_load_dword v132, v[12:13], off
	v_readlane_b32 s2, v59, 0
	s_ashr_i32 s3, s2, 31
	v_fma_f32 v8, -v17, v18, 1.0
	v_fmac_f32_e32 v18, v8, v18
	v_div_scale_f32 v8, vcc, s64, v16, s64
	v_mul_f32_e32 v9, v8, v18
	v_fma_f32 v10, -v17, v9, v8
	v_fmac_f32_e32 v9, v10, v18
	v_fma_f32 v8, -v17, v9, v8
	v_div_fmas_f32 v8, v8, v18, v9
	v_div_fixup_f32 v41, v8, v16, s64
	v_mul_f32_e32 v8, v41, v84
	v_rndne_f32_e32 v8, v8
	v_cvt_i32_f32_e32 v43, v8
	v_mul_f32_e32 v8, v41, v85
	v_rndne_f32_e32 v8, v8
	v_cvt_i32_f32_e32 v44, v8
	v_mul_f32_e32 v8, v41, v86
	s_lshl_b64 s[76:77], s[2:3], 11
	s_lshl_b64 s[2:3], s[2:3], 2
	v_rndne_f32_e32 v45, v8
	v_lshl_add_u64 v[8:9], v[64:65], 0, s[76:77]
	v_lshl_add_u64 v[12:13], v[66:67], 0, s[76:77]
	s_add_u32 s76, s44, s2
	s_addc_u32 s77, s45, s3
	s_add_u32 s2, s46, s2
	s_addc_u32 s3, s47, s3
	s_ashr_i32 s79, s78, 31
	s_lshl_b64 s[80:81], s[78:79], 11
	s_lshl_b64 s[78:79], s[78:79], 2
	v_mul_f32_e32 v42, 0x3c010204, v16
	v_lshl_add_u64 v[16:17], v[64:65], 0, s[80:81]
	v_lshl_add_u64 v[20:21], v[66:67], 0, s[80:81]
	s_add_u32 s80, s44, s78
	s_addc_u32 s81, s45, s79
	s_add_u32 s78, s46, s78
	s_addc_u32 s79, s47, s79
	s_ashr_i32 s83, s82, 31
	s_lshl_b64 s[84:85], s[82:83], 11
	s_lshl_b64 s[82:83], s[82:83], 2
	v_lshl_add_u64 v[24:25], v[64:65], 0, s[84:85]
	v_lshl_add_u64 v[26:27], v[66:67], 0, s[84:85]
	s_add_u32 s84, s44, s82
	s_addc_u32 s85, s45, s83
	s_add_u32 s82, s46, s82
	s_addc_u32 s83, s47, s83
	s_ashr_i32 s87, s86, 31
	s_lshl_b64 s[88:89], s[86:87], 11
	s_lshl_b64 s[86:87], s[86:87], 2
	v_lshl_add_u64 v[28:29], v[64:65], 0, s[88:89]
	v_lshl_add_u64 v[30:31], v[66:67], 0, s[88:89]
	s_add_u32 s88, s44, s86
	s_addc_u32 s89, s45, s87
	s_add_u32 s86, s46, s86
	global_load_dwordx4 v[8:11], v[8:9], off
	s_nop 0
	global_load_dwordx4 v[12:15], v[12:13], off
	s_nop 0
	global_load_dwordx4 v[16:19], v[16:17], off
	s_nop 0
	global_load_dwordx4 v[20:23], v[20:21], off
	s_nop 0
	global_load_dwordx4 v[32:35], v[24:25], off
	s_nop 0
	global_load_dwordx4 v[24:27], v[26:27], off
	s_nop 0
	global_load_dwordx4 v[36:39], v[28:29], off
	s_nop 0
	global_load_dwordx4 v[28:31], v[30:31], off
	s_addc_u32 s87, s47, s87
	global_load_dword v138, v57, s[76:77]
	global_load_dword v143, v57, s[2:3]
	global_load_dword v139, v57, s[80:81]
	global_load_dword v144, v57, s[78:79]
	global_load_dword v140, v57, s[84:85]
	global_load_dword v145, v57, s[82:83]
	global_load_dword v141, v57, s[88:89]
	global_load_dword v146, v57, s[86:87]
	v_mul_f32_e32 v46, v41, v87
	v_cvt_i32_f32_sdwa v45, v45 dst_sel:WORD_1 dst_unused:UNUSED_PAD src0_sel:DWORD
	v_rndne_f32_e32 v46, v46
	v_cvt_i32_f32_sdwa v46, v46 dst_sel:BYTE_3 dst_unused:UNUSED_PAD src0_sel:DWORD
	v_lshlrev_b32_e32 v44, 8, v44
	v_perm_b32 v43, v44, v43, s65
	v_and_b32_e32 v44, 0xff0000, v45
	v_or3_b32 v133, v43, v44, v46
	v_mul_f32_e32 v44, v41, v81
	v_mul_f32_e32 v43, v41, v80
	v_rndne_f32_e32 v44, v44
	v_mul_f32_e32 v45, v41, v82
	v_rndne_f32_e32 v43, v43
	v_cvt_i32_f32_e32 v44, v44
	v_rndne_f32_e32 v45, v45
	v_mul_f32_e32 v46, v41, v83
	v_cvt_i32_f32_e32 v43, v43
	v_cvt_i32_f32_sdwa v45, v45 dst_sel:WORD_1 dst_unused:UNUSED_PAD src0_sel:DWORD
	v_rndne_f32_e32 v46, v46
	v_cvt_i32_f32_sdwa v46, v46 dst_sel:BYTE_3 dst_unused:UNUSED_PAD src0_sel:DWORD
	v_lshlrev_b32_e32 v44, 8, v44
	v_perm_b32 v43, v44, v43, s65
	v_and_b32_e32 v44, 0xff0000, v45
	v_or3_b32 v134, v43, v44, v46
	v_mul_f32_e32 v44, v41, v77
	v_mul_f32_e32 v43, v41, v76
	v_rndne_f32_e32 v44, v44
	v_mul_f32_e32 v45, v41, v78
	v_rndne_f32_e32 v43, v43
	v_cvt_i32_f32_e32 v44, v44
	v_rndne_f32_e32 v45, v45
	v_mul_f32_e32 v46, v41, v79
	v_cvt_i32_f32_e32 v43, v43
	v_cvt_i32_f32_sdwa v45, v45 dst_sel:WORD_1 dst_unused:UNUSED_PAD src0_sel:DWORD
	v_rndne_f32_e32 v46, v46
	v_cvt_i32_f32_sdwa v46, v46 dst_sel:BYTE_3 dst_unused:UNUSED_PAD src0_sel:DWORD
	v_lshlrev_b32_e32 v44, 8, v44
	v_perm_b32 v43, v44, v43, s65
	v_and_b32_e32 v44, 0xff0000, v45
	v_or3_b32 v135, v43, v44, v46
	v_mul_f32_e32 v44, v41, v73
	v_mul_f32_e32 v43, v41, v72
	v_rndne_f32_e32 v44, v44
	v_mul_f32_e32 v45, v41, v74
	v_rndne_f32_e32 v43, v43
	v_cvt_i32_f32_e32 v44, v44
	v_rndne_f32_e32 v45, v45
	v_mul_f32_e32 v41, v41, v75
	v_cvt_i32_f32_e32 v43, v43
	v_cvt_i32_f32_sdwa v45, v45 dst_sel:WORD_1 dst_unused:UNUSED_PAD src0_sel:DWORD
	v_rndne_f32_e32 v41, v41
	v_cvt_i32_f32_sdwa v41, v41 dst_sel:BYTE_3 dst_unused:UNUSED_PAD src0_sel:DWORD
	v_lshlrev_b32_e32 v44, 8, v44
	v_perm_b32 v43, v44, v43, s65
	v_and_b32_e32 v44, 0xff0000, v45
	v_or3_b32 v136, v43, v44, v41
	v_readlane_b32 s40, v128, 3
	v_mul_f32_e32 v137, v40, v42
	s_mov_b32 s25, -4
	v_mov_b32_e32 v142, 0
	v_mov_b32_e32 v104, 0
	v_mov_b32_e32 v105, 0
	v_mov_b32_e32 v102, 0
	v_mov_b32_e32 v103, 0
	v_mov_b32_e32 v98, 0
	v_mov_b32_e32 v99, 0
	v_mov_b32_e32 v100, 0
	v_mov_b32_e32 v101, 0
	v_mov_b32_e32 v94, 0
	v_mov_b32_e32 v95, 0
	v_mov_b32_e32 v96, 0
	v_mov_b32_e32 v97, 0
	v_mov_b32_e32 v90, 0
	v_mov_b32_e32 v91, 0
	v_mov_b32_e32 v92, 0
	v_mov_b32_e32 v93, 0
.LBB0_474:
	s_cmp_lt_u32 s96, 8
	s_cbranch_scc0 .Lnopub_0
	v_cmp_eq_u32_e32 vcc, 0, v58
	s_add_i32 s32, s25, 4
	s_lshl_b32 s32, s32, 7
	s_add_i32 s32, s32, s97
	s_and_b32 s32, s32, 0x3fff
	v_mov_b32_e32 v239, s32
	s_and_b64 exec, vcc, 1
	global_store_dword v[224:225], v239, off
	s_mov_b64 exec, -1

.LBB0_600:
	s_waitcnt vmcnt(0)
	s_and_b32 s2, s96, 7
	s_lshl_b32 s2, s2, 7
	s_add_u32 s2, s2, s44
	s_addc_u32 s3, s45, 0
	s_add_u32 s2, s2, 0xffff8100
	s_addc_u32 s3, s3, -1
	v_mov_b32_e32 v224, s2
	v_mov_b32_e32 v225, s3
	global_load_dword v234, v[224:225], off sc1
	v_lshl_or_b32 v226, v59, 7, v60
	v_lshlrev_b32_e32 v227, 7, v89
	v_or3_b32 v227, v227, v60, 64
	ds_bpermute_b32 v228, v122, v226
	ds_bpermute_b32 v229, v122, v227
	s_mov_b32 vcc_lo, 0x99999999
	s_mov_b32 vcc_hi, 0x99999999
	s_waitcnt lgkmcnt(0)
	v_min_u32_e32 v230, v226, v228
	v_max_u32_e32 v231, v226, v228
	v_min_u32_e32 v232, v227, v229
	v_max_u32_e32 v233, v227, v229
	v_cndmask_b32_e32 v226, v231, v230, vcc
	v_cndmask_b32_e32 v227, v233, v232, vcc
	ds_bpermute_b32 v228, v123, v226
	ds_bpermute_b32 v229, v123, v227
	s_mov_b32 vcc_lo, 0xc3c3c3c3
	s_mov_b32 vcc_hi, 0xc3c3c3c3
	s_waitcnt lgkmcnt(0)
	v_min_u32_e32 v230, v226, v228
	v_max_u32_e32 v231, v226, v228
	v_min_u32_e32 v232, v227, v229
	v_max_u32_e32 v233, v227, v229
	v_cndmask_b32_e32 v226, v231, v230, vcc
	v_cndmask_b32_e32 v227, v233, v232, vcc
	ds_bpermute_b32 v228, v122, v226
	ds_bpermute_b32 v229, v122, v227
	s_mov_b32 vcc_lo, 0xa5a5a5a5
	s_mov_b32 vcc_hi, 0xa5a5a5a5
	s_waitcnt lgkmcnt(0)
	v_min_u32_e32 v230, v226, v228
	v_max_u32_e32 v231, v226, v228
	v_min_u32_e32 v232, v227, v229
	v_max_u32_e32 v233, v227, v229
	v_cndmask_b32_e32 v226, v231, v230, vcc
	v_cndmask_b32_e32 v227, v233, v232, vcc
	ds_bpermute_b32 v228, v124, v226
	ds_bpermute_b32 v229, v124, v227
	s_mov_b32 vcc_lo, 0xf00ff00f
	s_mov_b32 vcc_hi, 0xf00ff00f
	s_waitcnt lgkmcnt(0)
	v_min_u32_e32 v230, v226, v228
	v_max_u32_e32 v231, v226, v228
	v_min_u32_e32 v232, v227, v229
	v_max_u32_e32 v233, v227, v229
	v_cndmask_b32_e32 v226, v231, v230, vcc
	v_cndmask_b32_e32 v227, v233, v232, vcc
	ds_bpermute_b32 v228, v123, v226
	ds_bpermute_b32 v229, v123, v227
	s_mov_b32 vcc_lo, 0xcc33cc33
	s_mov_b32 vcc_hi, 0xcc33cc33
	s_waitcnt lgkmcnt(0)
	v_min_u32_e32 v230, v226, v228
	v_max_u32_e32 v231, v226, v228
	v_min_u32_e32 v232, v227, v229
	v_max_u32_e32 v233, v227, v229
	v_cndmask_b32_e32 v226, v231, v230, vcc
	v_cndmask_b32_e32 v227, v233, v232, vcc
	ds_bpermute_b32 v228, v122, v226
	ds_bpermute_b32 v229, v122, v227
	s_mov_b32 vcc_lo, 0xaa55aa55
	s_mov_b32 vcc_hi, 0xaa55aa55
	s_waitcnt lgkmcnt(0)
	v_min_u32_e32 v230, v226, v228
	v_max_u32_e32 v231, v226, v228
	v_min_u32_e32 v232, v227, v229
	v_max_u32_e32 v233, v227, v229
	v_cndmask_b32_e32 v226, v231, v230, vcc
	v_cndmask_b32_e32 v227, v233, v232, vcc
	ds_bpermute_b32 v228, v125, v226
	ds_bpermute_b32 v229, v125, v227
	s_mov_b32 vcc_lo, 0xff0000ff
	s_mov_b32 vcc_hi, 0xff0000ff
	s_waitcnt lgkmcnt(0)
	v_min_u32_e32 v230, v226, v228
	v_max_u32_e32 v231, v226, v228
	v_min_u32_e32 v232, v227, v229
	v_max_u32_e32 v233, v227, v229
	v_cndmask_b32_e32 v226, v231, v230, vcc
	v_cndmask_b32_e32 v227, v233, v232, vcc
	ds_bpermute_b32 v228, v124, v226
	ds_bpermute_b32 v229, v124, v227
	s_mov_b32 vcc_lo, 0xf0f00f0f
	s_mov_b32 vcc_hi, 0xf0f00f0f
	s_waitcnt lgkmcnt(0)
	v_min_u32_e32 v230, v226, v228
	v_max_u32_e32 v231, v226, v228
	v_min_u32_e32 v232, v227, v229
	v_max_u32_e32 v233, v227, v229
	v_cndmask_b32_e32 v226, v231, v230, vcc
	v_cndmask_b32_e32 v227, v233, v232, vcc
	ds_bpermute_b32 v228, v123, v226
	ds_bpermute_b32 v229, v123, v227
	s_mov_b32 vcc_lo, 0xcccc3333
	s_mov_b32 vcc_hi, 0xcccc3333
	s_waitcnt lgkmcnt(0)
	v_min_u32_e32 v230, v226, v228
	v_max_u32_e32 v231, v226, v228
	v_min_u32_e32 v232, v227, v229
	v_max_u32_e32 v233, v227, v229
	v_cndmask_b32_e32 v226, v231, v230, vcc
	v_cndmask_b32_e32 v227, v233, v232, vcc
	ds_bpermute_b32 v228, v122, v226
	ds_bpermute_b32 v229, v122, v227
	s_mov_b32 vcc_lo, 0xaaaa5555
	s_mov_b32 vcc_hi, 0xaaaa5555
	s_waitcnt lgkmcnt(0)
	v_min_u32_e32 v230, v226, v228
	v_max_u32_e32 v231, v226, v228
	v_min_u32_e32 v232, v227, v229
	v_max_u32_e32 v233, v227, v229
	v_cndmask_b32_e32 v226, v231, v230, vcc
	v_cndmask_b32_e32 v227, v233, v232, vcc
	ds_bpermute_b32 v228, v126, v226
	ds_bpermute_b32 v229, v126, v227
	s_mov_b32 vcc_lo, 0x0000ffff
	s_mov_b32 vcc_hi, 0xffff0000
	s_waitcnt lgkmcnt(0)
	v_min_u32_e32 v230, v226, v228
	v_max_u32_e32 v231, v226, v228
	v_min_u32_e32 v232, v227, v229
	v_max_u32_e32 v233, v227, v229
	v_cndmask_b32_e32 v226, v231, v230, vcc
	v_cndmask_b32_e32 v227, v233, v232, vcc
	ds_bpermute_b32 v228, v125, v226
	ds_bpermute_b32 v229, v125, v227
	s_mov_b32 vcc_lo, 0x00ff00ff
	s_mov_b32 vcc_hi, 0xff00ff00
	s_waitcnt lgkmcnt(0)
	v_min_u32_e32 v230, v226, v228
	v_max_u32_e32 v231, v226, v228
	v_min_u32_e32 v232, v227, v229
	v_max_u32_e32 v233, v227, v229
	v_cndmask_b32_e32 v226, v231, v230, vcc
	v_cndmask_b32_e32 v227, v233, v232, vcc
	ds_bpermute_b32 v228, v124, v226
	ds_bpermute_b32 v229, v124, v227
	s_mov_b32 vcc_lo, 0x0f0f0f0f
	s_mov_b32 vcc_hi, 0xf0f0f0f0
	s_waitcnt lgkmcnt(0)
	v_min_u32_e32 v230, v226, v228
	v_max_u32_e32 v231, v226, v228
	v_min_u32_e32 v232, v227, v229
	v_max_u32_e32 v233, v227, v229
	v_cndmask_b32_e32 v226, v231, v230, vcc
	v_cndmask_b32_e32 v227, v233, v232, vcc
	ds_bpermute_b32 v228, v123, v226
	ds_bpermute_b32 v229, v123, v227
	s_mov_b32 vcc_lo, 0x33333333
	s_mov_b32 vcc_hi, 0xcccccccc
	s_waitcnt lgkmcnt(0)
	v_min_u32_e32 v230, v226, v228
	v_max_u32_e32 v231, v226, v228
	v_min_u32_e32 v232, v227, v229
	v_max_u32_e32 v233, v227, v229
	v_cndmask_b32_e32 v226, v231, v230, vcc
	v_cndmask_b32_e32 v227, v233, v232, vcc
	ds_bpermute_b32 v228, v122, v226
	ds_bpermute_b32 v229, v122, v227
	s_mov_b32 vcc_lo, 0x55555555
	s_mov_b32 vcc_hi, 0xaaaaaaaa
	s_waitcnt lgkmcnt(0)
	v_min_u32_e32 v230, v226, v228
	v_max_u32_e32 v231, v226, v228
	v_min_u32_e32 v232, v227, v229
	v_max_u32_e32 v233, v227, v229
	v_cndmask_b32_e32 v226, v231, v230, vcc
	v_cndmask_b32_e32 v227, v233, v232, vcc
	ds_bpermute_b32 v228, v127, v226
	ds_bpermute_b32 v229, v127, v227
	s_mov_b32 vcc_lo, 0xffffffff
	s_mov_b32 vcc_hi, 0x00000000
	s_waitcnt lgkmcnt(0)
	v_min_u32_e32 v230, v226, v228
	v_max_u32_e32 v231, v226, v228
	v_min_u32_e32 v232, v227, v229
	v_max_u32_e32 v233, v227, v229
	v_cndmask_b32_e32 v226, v231, v230, vcc
	v_cndmask_b32_e32 v227, v232, v233, vcc
	ds_bpermute_b32 v228, v126, v226
	ds_bpermute_b32 v229, v126, v227
	s_mov_b32 vcc_lo, 0x0000ffff
	s_mov_b32 vcc_hi, 0x0000ffff
	s_waitcnt lgkmcnt(0)
	v_min_u32_e32 v230, v226, v228
	v_max_u32_e32 v231, v226, v228
	v_min_u32_e32 v232, v227, v229
	v_max_u32_e32 v233, v227, v229
	v_cndmask_b32_e32 v226, v231, v230, vcc
	v_cndmask_b32_e32 v227, v232, v233, vcc
	ds_bpermute_b32 v228, v125, v226
	ds_bpermute_b32 v229, v125, v227
	s_mov_b32 vcc_lo, 0x00ff00ff
	s_mov_b32 vcc_hi, 0x00ff00ff
	s_waitcnt lgkmcnt(0)
	v_min_u32_e32 v230, v226, v228
	v_max_u32_e32 v231, v226, v228
	v_min_u32_e32 v232, v227, v229
	v_max_u32_e32 v233, v227, v229
	v_cndmask_b32_e32 v226, v231, v230, vcc
	v_cndmask_b32_e32 v227, v232, v233, vcc
	ds_bpermute_b32 v228, v124, v226
	ds_bpermute_b32 v229, v124, v227
	s_mov_b32 vcc_lo, 0x0f0f0f0f
	s_mov_b32 vcc_hi, 0x0f0f0f0f
	s_waitcnt lgkmcnt(0)
	v_min_u32_e32 v230, v226, v228
	v_max_u32_e32 v231, v226, v228
	v_min_u32_e32 v232, v227, v229
	v_max_u32_e32 v233, v227, v229
	v_cndmask_b32_e32 v226, v231, v230, vcc
	v_cndmask_b32_e32 v227, v232, v233, vcc
	ds_bpermute_b32 v228, v123, v226
	ds_bpermute_b32 v229, v123, v227
	s_mov_b32 vcc_lo, 0x33333333
	s_mov_b32 vcc_hi, 0x33333333
	s_waitcnt lgkmcnt(0)
	v_min_u32_e32 v230, v226, v228
	v_max_u32_e32 v231, v226, v228
	v_min_u32_e32 v232, v227, v229
	v_max_u32_e32 v233, v227, v229
	v_cndmask_b32_e32 v226, v231, v230, vcc
	v_cndmask_b32_e32 v227, v232, v233, vcc
	ds_bpermute_b32 v228, v122, v226
	ds_bpermute_b32 v229, v122, v227
	s_mov_b32 vcc_lo, 0x55555555
	s_mov_b32 vcc_hi, 0x55555555
	s_waitcnt lgkmcnt(0)
	v_min_u32_e32 v230, v226, v228
	v_max_u32_e32 v231, v226, v228
	v_min_u32_e32 v232, v227, v229
	v_max_u32_e32 v233, v227, v229
	v_cndmask_b32_e32 v226, v231, v230, vcc
	v_cndmask_b32_e32 v227, v232, v233, vcc
	v_min_u32_e32 v230, v226, v227
	v_max_u32_e32 v227, v226, v227
	v_mov_b32_e32 v226, v230
	ds_bpermute_b32 v228, v127, v226
	ds_bpermute_b32 v229, v127, v227
	s_mov_b32 vcc_lo, 0xffffffff
	s_mov_b32 vcc_hi, 0x00000000
	s_waitcnt lgkmcnt(0)
	v_min_u32_e32 v230, v226, v228
	v_max_u32_e32 v231, v226, v228
	v_min_u32_e32 v232, v227, v229
	v_max_u32_e32 v233, v227, v229
	v_cndmask_b32_e32 v226, v231, v230, vcc
	v_cndmask_b32_e32 v227, v233, v232, vcc
	ds_bpermute_b32 v228, v126, v226
	ds_bpermute_b32 v229, v126, v227
	s_mov_b32 vcc_lo, 0x0000ffff
	s_mov_b32 vcc_hi, 0x0000ffff
	s_waitcnt lgkmcnt(0)
	v_min_u32_e32 v230, v226, v228
	v_max_u32_e32 v231, v226, v228
	v_min_u32_e32 v232, v227, v229
	v_max_u32_e32 v233, v227, v229
	v_cndmask_b32_e32 v226, v231, v230, vcc
	v_cndmask_b32_e32 v227, v233, v232, vcc
	ds_bpermute_b32 v228, v125, v226
	ds_bpermute_b32 v229, v125, v227
	s_mov_b32 vcc_lo, 0x00ff00ff
	s_mov_b32 vcc_hi, 0x00ff00ff
	s_waitcnt lgkmcnt(0)
	v_min_u32_e32 v230, v226, v228
	v_max_u32_e32 v231, v226, v228
	v_min_u32_e32 v232, v227, v229
	v_max_u32_e32 v233, v227, v229
	v_cndmask_b32_e32 v226, v231, v230, vcc
	v_cndmask_b32_e32 v227, v233, v232, vcc
	ds_bpermute_b32 v228, v124, v226
	ds_bpermute_b32 v229, v124, v227
	s_mov_b32 vcc_lo, 0x0f0f0f0f
	s_mov_b32 vcc_hi, 0x0f0f0f0f
	s_waitcnt lgkmcnt(0)
	v_min_u32_e32 v230, v226, v228
	v_max_u32_e32 v231, v226, v228
	v_min_u32_e32 v232, v227, v229
	v_max_u32_e32 v233, v227, v229
	v_cndmask_b32_e32 v226, v231, v230, vcc
	v_cndmask_b32_e32 v227, v233, v232, vcc
	ds_bpermute_b32 v228, v123, v226
	ds_bpermute_b32 v229, v123, v227
	s_mov_b32 vcc_lo, 0x33333333
	s_mov_b32 vcc_hi, 0x33333333
	s_waitcnt lgkmcnt(0)
	v_min_u32_e32 v230, v226, v228
	v_max_u32_e32 v231, v226, v228
	v_min_u32_e32 v232, v227, v229
	v_max_u32_e32 v233, v227, v229
	v_cndmask_b32_e32 v226, v231, v230, vcc
	v_cndmask_b32_e32 v227, v233, v232, vcc
	ds_bpermute_b32 v228, v122, v226
	ds_bpermute_b32 v229, v122, v227
	s_mov_b32 vcc_lo, 0x55555555
	s_mov_b32 vcc_hi, 0x55555555
	s_waitcnt lgkmcnt(0)
	v_min_u32_e32 v230, v226, v228
	v_max_u32_e32 v231, v226, v228
	v_min_u32_e32 v232, v227, v229
	v_max_u32_e32 v233, v227, v229
	v_cndmask_b32_e32 v226, v231, v230, vcc
	v_cndmask_b32_e32 v227, v233, v232, vcc
	s_waitcnt vmcnt(0)
	v_readfirstlane_b32 s2, v234
	s_and_b32 s2, s2, 0x3fff
	s_mov_b32 s97, s2
	s_lshl_b32 s3, s2, 7
	v_cmp_gt_u32_e32 vcc, s3, v226
	s_nop 1
	s_bcnt1_i32_b64 s2, vcc
	v_cmp_gt_u32_e32 vcc, s3, v227
	s_nop 1
	s_bcnt1_i32_b64 s3, vcc
	s_add_i32 s2, s2, s3
	s_and_b32 s2, s2, 0x7c
	v_add_u32_e32 v235, s2, v60
	v_and_b32_e32 v235, 0x7f, v235
	v_and_b32_e32 v236, 63, v235
	v_lshlrev_b32_e32 v236, 2, v236
	ds_bpermute_b32 v228, v236, v226
	ds_bpermute_b32 v229, v236, v227
	v_cmp_gt_u32_e32 vcc, 64, v235
	s_waitcnt lgkmcnt(0)
	v_cndmask_b32_e32 v230, v229, v228, vcc
	v_cndmask_b32_e32 v231, v228, v229, vcc
	v_lshrrev_b32_e32 v59, 7, v230
	v_lshrrev_b32_e32 v89, 7, v231
	v_and_b32_e32 v235, 63, v230
	v_lshlrev_b32_e32 v235, 2, v235
	v_and_b32_e32 v236, 63, v231
	v_lshlrev_b32_e32 v236, 2, v236
	ds_bpermute_b32 v240, v235, v128
	ds_bpermute_b32 v241, v235, v129
	ds_bpermute_b32 v242, v236, v128
	ds_bpermute_b32 v243, v236, v129
	v_and_b32_e32 v237, 64, v230
	v_and_b32_e32 v238, 64, v231
	s_waitcnt lgkmcnt(0)
	v_cmp_eq_u32_e32 vcc, 0, v237
	s_nop 1
	v_cndmask_b32_e32 v128, v241, v240, vcc
	v_cmp_eq_u32_e32 vcc, 0, v238
	s_nop 1
	v_cndmask_b32_e32 v129, v243, v242, vcc
	s_nop 1
	v_lshlrev_b32_e32 v84, 16, v4
	v_and_b32_e32 v85, 0xffff0000, v4
	v_lshlrev_b32_e32 v86, 16, v5
	v_and_b32_e32 v87, 0xffff0000, v5
	v_lshlrev_b32_e32 v76, 16, v0
	v_and_b32_e32 v77, 0xffff0000, v0
	v_max3_f32 v0, |v84|, 0, |v85|
	v_lshlrev_b32_e32 v80, 16, v6
	v_and_b32_e32 v81, 0xffff0000, v6
	v_max3_f32 v0, v0, |v86|, |v87|
	v_lshlrev_b32_e32 v82, 16, v7
	v_and_b32_e32 v83, 0xffff0000, v7
	v_max3_f32 v0, v0, |v80|, |v81|
	v_max3_f32 v0, v0, |v82|, |v83|
	v_lshlrev_b32_e32 v78, 16, v1
	v_and_b32_e32 v79, 0xffff0000, v1
	v_max3_f32 v0, v0, |v76|, |v77|
	v_lshlrev_b32_e32 v72, 16, v2
	v_and_b32_e32 v73, 0xffff0000, v2
	v_max3_f32 v0, v0, |v78|, |v79|
	v_lshlrev_b32_e32 v74, 16, v3
	v_and_b32_e32 v75, 0xffff0000, v3
	v_max3_f32 v0, v0, |v72|, |v73|
	v_max3_f32 v0, v0, |v74|, |v75|
	ds_bpermute_b32 v1, v127, v0
	v_or_b32_e32 v88, s23, v58
	s_add_i32 s23, s23, 1
	s_min_u32 s2, s23, 15
	v_or_b32_e32 v8, s2, v62
	s_waitcnt lgkmcnt(0)
	v_max_f32_e32 v1, v1, v1
	v_max_f32_e32 v0, v0, v1
	ds_bpermute_b32 v1, v126, v0
	v_mov_b32_e32 v9, v63
	v_lshl_add_u32 v2, v88, 2, v118
	ds_read_b32 v40, v2
	s_waitcnt vmcnt(3)
	v_readlane_b32 s76, v59, 1
	s_waitcnt lgkmcnt(1)
	v_max_f32_e32 v1, v1, v1
	v_max_f32_e32 v0, v0, v1
	ds_bpermute_b32 v1, v125, v0
	v_readlane_b32 s80, v59, 2
	v_readlane_b32 s84, v59, 3
	s_waitcnt vmcnt(1)
	v_readlane_b32 s33, v128, 0
	v_readlane_b32 s38, v128, 3
	s_waitcnt lgkmcnt(0)
	v_max_f32_e32 v1, v1, v1
	v_max_f32_e32 v10, v0, v1
	ds_bpermute_b32 v11, v124, v10
	v_lshlrev_b64 v[0:1], 11, v[8:9]
	v_lshlrev_b64 v[8:9], 9, v[8:9]
	v_lshl_or_b32 v8, v60, 2, v8
	v_lshl_add_u64 v[4:5], v[70:71], 0, v[0:1]
	s_waitcnt lgkmcnt(0)
	v_max_f32_e32 v11, v11, v11
	v_max_f32_e32 v13, v10, v11
	ds_bpermute_b32 v14, v123, v13
	v_lshl_add_u64 v[10:11], s[12:13], 0, v[8:9]
	v_or_b32_e32 v12, 0x100, v8
	global_load_dwordx4 v[0:3], v[4:5], off offset:16
	s_nop 0
	global_load_dwordx4 v[4:7], v[4:5], off
	s_mov_b32 s25, -4
	s_waitcnt lgkmcnt(0)
	v_max_f32_e32 v14, v14, v14
	v_max_f32_e32 v16, v13, v14
	ds_bpermute_b32 v17, v122, v16
	v_mov_b32_e32 v13, v9
	v_lshl_add_u64 v[8:9], s[14:15], 0, v[8:9]
	v_lshl_add_u64 v[14:15], s[12:13], 0, v[12:13]
	v_lshl_add_u64 v[12:13], s[14:15], 0, v[12:13]
	s_waitcnt lgkmcnt(0)
	v_max3_f32 v16, v16, v17, s63
	v_div_scale_f32 v17, s[2:3], v16, v16, s64
	v_rcp_f32_e32 v18, v17
	global_load_dword v56, v[10:11], off
	global_load_dword v130, v[14:15], off
	global_load_dword v131, v[8:9], off
	global_load_dword v132, v[12:13], off
	v_readlane_b32 s2, v59, 0
	s_ashr_i32 s3, s2, 31
	v_fma_f32 v8, -v17, v18, 1.0
	v_fmac_f32_e32 v18, v8, v18
	v_div_scale_f32 v8, vcc, s64, v16, s64
	v_mul_f32_e32 v9, v8, v18
	v_fma_f32 v10, -v17, v9, v8
	v_fmac_f32_e32 v9, v10, v18
	v_fma_f32 v8, -v17, v9, v8
	v_div_fmas_f32 v8, v8, v18, v9
	v_div_fixup_f32 v41, v8, v16, s64
	v_mul_f32_e32 v8, v41, v84
	v_rndne_f32_e32 v8, v8
	v_cvt_i32_f32_e32 v43, v8
	v_mul_f32_e32 v8, v41, v85
	v_rndne_f32_e32 v8, v8
	v_cvt_i32_f32_e32 v44, v8
	v_mul_f32_e32 v8, v41, v86
	s_lshl_b64 s[36:37], s[2:3], 11
	s_lshl_b64 s[2:3], s[2:3], 2
	v_rndne_f32_e32 v45, v8
	v_lshl_add_u64 v[8:9], v[64:65], 0, s[36:37]
	v_lshl_add_u64 v[12:13], v[66:67], 0, s[36:37]
	s_add_u32 s36, s44, s2
	s_addc_u32 s37, s45, s3
	s_add_u32 s2, s46, s2
	s_addc_u32 s3, s47, s3
	s_ashr_i32 s77, s76, 31
	s_lshl_b64 s[78:79], s[76:77], 11
	s_lshl_b64 s[76:77], s[76:77], 2
	v_mul_f32_e32 v42, 0x3c010204, v16
	v_lshl_add_u64 v[16:17], v[64:65], 0, s[78:79]
	v_lshl_add_u64 v[20:21], v[66:67], 0, s[78:79]
	s_add_u32 s78, s44, s76
	s_addc_u32 s79, s45, s77
	s_add_u32 s76, s46, s76
	s_addc_u32 s77, s47, s77
	s_ashr_i32 s81, s80, 31
	s_lshl_b64 s[82:83], s[80:81], 11
	s_lshl_b64 s[80:81], s[80:81], 2
	v_lshl_add_u64 v[24:25], v[64:65], 0, s[82:83]
	v_lshl_add_u64 v[26:27], v[66:67], 0, s[82:83]
	s_add_u32 s82, s44, s80
	s_addc_u32 s83, s45, s81
	s_add_u32 s80, s46, s80
	s_addc_u32 s81, s47, s81
	s_ashr_i32 s85, s84, 31
	s_lshl_b64 s[86:87], s[84:85], 11
	s_lshl_b64 s[84:85], s[84:85], 2
	v_lshl_add_u64 v[28:29], v[64:65], 0, s[86:87]
	v_lshl_add_u64 v[30:31], v[66:67], 0, s[86:87]
	s_add_u32 s86, s44, s84
	s_addc_u32 s87, s45, s85
	s_add_u32 s84, s46, s84
	global_load_dwordx4 v[8:11], v[8:9], off
	s_nop 0
	global_load_dwordx4 v[12:15], v[12:13], off
	s_nop 0
	global_load_dwordx4 v[16:19], v[16:17], off
	s_nop 0
	global_load_dwordx4 v[20:23], v[20:21], off
	s_nop 0
	global_load_dwordx4 v[32:35], v[24:25], off
	s_nop 0
	global_load_dwordx4 v[24:27], v[26:27], off
	s_nop 0
	global_load_dwordx4 v[36:39], v[28:29], off
	s_nop 0
	global_load_dwordx4 v[28:31], v[30:31], off
	s_addc_u32 s85, s47, s85
	global_load_dword v138, v57, s[36:37]
	global_load_dword v143, v57, s[2:3]
	global_load_dword v139, v57, s[78:79]
	global_load_dword v144, v57, s[76:77]
	global_load_dword v140, v57, s[82:83]
	global_load_dword v145, v57, s[80:81]
	global_load_dword v141, v57, s[86:87]
	global_load_dword v146, v57, s[84:85]
	v_mul_f32_e32 v46, v41, v87
	v_cvt_i32_f32_sdwa v45, v45 dst_sel:WORD_1 dst_unused:UNUSED_PAD src0_sel:DWORD
	v_rndne_f32_e32 v46, v46
	v_cvt_i32_f32_sdwa v46, v46 dst_sel:BYTE_3 dst_unused:UNUSED_PAD src0_sel:DWORD
	v_lshlrev_b32_e32 v44, 8, v44
	v_perm_b32 v43, v44, v43, s65
	v_and_b32_e32 v44, 0xff0000, v45
	v_or3_b32 v133, v43, v44, v46
	v_mul_f32_e32 v44, v41, v81
	v_mul_f32_e32 v43, v41, v80
	v_rndne_f32_e32 v44, v44
	v_mul_f32_e32 v45, v41, v82
	v_rndne_f32_e32 v43, v43
	v_cvt_i32_f32_e32 v44, v44
	v_rndne_f32_e32 v45, v45
	v_mul_f32_e32 v46, v41, v83
	v_cvt_i32_f32_e32 v43, v43
	v_cvt_i32_f32_sdwa v45, v45 dst_sel:WORD_1 dst_unused:UNUSED_PAD src0_sel:DWORD
	v_rndne_f32_e32 v46, v46
	v_cvt_i32_f32_sdwa v46, v46 dst_sel:BYTE_3 dst_unused:UNUSED_PAD src0_sel:DWORD
	v_lshlrev_b32_e32 v44, 8, v44
	v_perm_b32 v43, v44, v43, s65
	v_and_b32_e32 v44, 0xff0000, v45
	v_or3_b32 v134, v43, v44, v46
	v_mul_f32_e32 v44, v41, v77
	v_mul_f32_e32 v43, v41, v76
	v_rndne_f32_e32 v44, v44
	v_mul_f32_e32 v45, v41, v78
	v_rndne_f32_e32 v43, v43
	v_cvt_i32_f32_e32 v44, v44
	v_rndne_f32_e32 v45, v45
	v_mul_f32_e32 v46, v41, v79
	v_cvt_i32_f32_e32 v43, v43
	v_cvt_i32_f32_sdwa v45, v45 dst_sel:WORD_1 dst_unused:UNUSED_PAD src0_sel:DWORD
	v_rndne_f32_e32 v46, v46
	v_cvt_i32_f32_sdwa v46, v46 dst_sel:BYTE_3 dst_unused:UNUSED_PAD src0_sel:DWORD
	v_lshlrev_b32_e32 v44, 8, v44
	v_perm_b32 v43, v44, v43, s65
	v_and_b32_e32 v44, 0xff0000, v45
	v_or3_b32 v135, v43, v44, v46
	v_mul_f32_e32 v44, v41, v73
	v_mul_f32_e32 v43, v41, v72
	v_rndne_f32_e32 v44, v44
	v_mul_f32_e32 v45, v41, v74
	v_rndne_f32_e32 v43, v43
	v_cvt_i32_f32_e32 v44, v44
	v_rndne_f32_e32 v45, v45
	v_mul_f32_e32 v41, v41, v75
	v_cvt_i32_f32_e32 v43, v43
	v_cvt_i32_f32_sdwa v45, v45 dst_sel:WORD_1 dst_unused:UNUSED_PAD src0_sel:DWORD
	v_rndne_f32_e32 v41, v41
	v_cvt_i32_f32_sdwa v41, v41 dst_sel:BYTE_3 dst_unused:UNUSED_PAD src0_sel:DWORD
	v_lshlrev_b32_e32 v44, 8, v44
	v_perm_b32 v43, v44, v43, s65
	v_and_b32_e32 v44, 0xff0000, v45
	v_or3_b32 v136, v43, v44, v41
	v_readlane_b32 s36, v128, 1
	v_readlane_b32 s37, v128, 2
	v_mul_f32_e32 v137, v40, v42
	v_mov_b32_e32 v142, 0
	v_mov_b32_e32 v104, 0
	v_mov_b32_e32 v105, 0
	v_mov_b32_e32 v102, 0
	v_mov_b32_e32 v103, 0
	v_mov_b32_e32 v98, 0
	v_mov_b32_e32 v99, 0
	v_mov_b32_e32 v100, 0
	v_mov_b32_e32 v101, 0
	v_mov_b32_e32 v94, 0
	v_mov_b32_e32 v95, 0
	v_mov_b32_e32 v96, 0
	v_mov_b32_e32 v97, 0
	v_mov_b32_e32 v90, 0
	v_mov_b32_e32 v91, 0
	v_mov_b32_e32 v92, 0
	v_mov_b32_e32 v93, 0
